# cmp pass 1 VALU section by hand: mask cmp/cndmask alternate two SGPR pairs (no hazard nops), per-row m_use select instead of per-element, same sums
# baseline (speedup 1.0000x reference)
.LBB0_794:
	v_mov_b32_e32 v32, v0
	v_cndmask_b32_e64 v0, 0, 1, s[0:1]
	s_mul_i32 s1, s13, 0x2400
	v_or_b32_e32 v8, s1, v70
	v_add_u32_e32 v9, v8, v71
	v_cmp_ne_u32_e32 vcc, 1, v0
	ds_read_b128 v[0:3], v9
	ds_read_b128 v[4:7], v9 offset:32
	s_waitcnt lgkmcnt(1)
	v_mfma_f32_32x32x16_bf16 v[16:31], v[0:3], v[112:115], 0
	ds_read_b128 v[0:3], v9 offset:64
	v_add_u32_e32 v43, v8, v72
	s_lshl_b32 s0, s13, 6
	s_sub_i32 s0, s11, s0
	v_mov_b32_e32 v42, v75
	s_and_b64 vcc, exec, vcc
	s_mov_b32 s13, 1
	s_waitcnt lgkmcnt(1)
	v_mfma_f32_32x32x16_bf16 v[16:31], v[4:7], v[116:119], v[16:31]
	s_waitcnt lgkmcnt(0)
	v_mfma_f32_32x32x16_bf16 v[16:31], v[0:3], v[120:123], v[16:31]
	ds_read_b128 v[0:3], v9 offset:96
	s_waitcnt lgkmcnt(0)
	v_mfma_f32_32x32x16_bf16 v[16:31], v[0:3], v[124:127], v[16:31]
	ds_read_b128 v[0:3], v43
	ds_read_b128 v[38:41], v43 offset:32
	s_waitcnt lgkmcnt(1)
	v_mfma_f32_32x32x16_bf16 v[0:15], v[0:3], v[112:115], 0
	s_waitcnt lgkmcnt(0)
	v_mfma_f32_32x32x16_bf16 v[0:15], v[38:41], v[116:119], v[0:15]
	ds_read_b128 v[38:41], v43 offset:64
	s_waitcnt lgkmcnt(0)
	v_mfma_f32_32x32x16_bf16 v[0:15], v[38:41], v[120:123], v[0:15]
	ds_read_b128 v[38:41], v43 offset:96
	s_waitcnt lgkmcnt(0)
	v_mfma_f32_32x32x16_bf16 v[0:15], v[38:41], v[124:127], v[0:15]
	v_add_u32_e32 v38, s0, v37
	v_cmp_lt_i32_e64 s[0:1], -1, v38
	v_cmp_lt_i32_e64 s[100:101], 0, v38
	s_nop 0
	v_cndmask_b32_e64 v16, v215, v16, s[0:1]
	v_cndmask_b32_e64 v17, v215, v17, s[100:101]
	v_cmp_lt_i32_e64 s[0:1], 1, v38
	v_cmp_lt_i32_e64 s[100:101], 2, v38
	v_max3_f32 v39, v16, s16, v17
	v_cndmask_b32_e64 v18, v215, v18, s[0:1]
	v_cndmask_b32_e64 v19, v215, v19, s[100:101]
	v_cmp_lt_i32_e64 s[0:1], 7, v38
	v_cmp_lt_i32_e64 s[100:101], 8, v38
	v_max3_f32 v39, v39, v18, v19
	v_cndmask_b32_e64 v20, v215, v20, s[0:1]
	v_cndmask_b32_e64 v21, v215, v21, s[100:101]
	v_cmp_lt_i32_e64 s[0:1], 9, v38
	v_cmp_lt_i32_e64 s[100:101], 10, v38
	v_max3_f32 v39, v39, v20, v21
	v_cndmask_b32_e64 v22, v215, v22, s[0:1]
	v_cndmask_b32_e64 v23, v215, v23, s[100:101]
	v_cmp_lt_i32_e64 s[0:1], 15, v38
	v_cmp_lt_i32_e64 s[100:101], 16, v38
	v_max3_f32 v39, v39, v22, v23
	v_cndmask_b32_e64 v24, v215, v24, s[0:1]
	v_cndmask_b32_e64 v25, v215, v25, s[100:101]
	v_cmp_lt_i32_e64 s[0:1], 17, v38
	v_cmp_lt_i32_e64 s[100:101], 18, v38
	v_max3_f32 v39, v39, v24, v25
	v_cndmask_b32_e64 v26, v215, v26, s[0:1]
	v_cndmask_b32_e64 v27, v215, v27, s[100:101]
	v_cmp_lt_i32_e64 s[0:1], 23, v38
	v_cmp_lt_i32_e64 s[100:101], 24, v38
	v_max3_f32 v39, v39, v26, v27
	v_cndmask_b32_e64 v28, v215, v28, s[0:1]
	v_cndmask_b32_e64 v29, v215, v29, s[100:101]
	v_cmp_lt_i32_e64 s[0:1], 25, v38
	v_cmp_lt_i32_e64 s[100:101], 26, v38
	v_max3_f32 v39, v39, v28, v29
	v_cndmask_b32_e64 v30, v215, v30, s[0:1]
	v_cndmask_b32_e64 v31, v215, v31, s[100:101]
	v_cmp_lt_i32_e64 s[0:1], 31, v38
	v_cmp_lt_i32_e64 s[100:101], 32, v38
	v_max3_f32 v39, v39, v30, v31
	v_cndmask_b32_e64 v0, v215, v0, s[0:1]
	v_cndmask_b32_e64 v1, v215, v1, s[100:101]
	v_cmp_lt_i32_e64 s[0:1], 33, v38
	v_cmp_lt_i32_e64 s[100:101], 34, v38
	v_max3_f32 v39, v39, v0, v1
	v_cndmask_b32_e64 v2, v215, v2, s[0:1]
	v_cndmask_b32_e64 v3, v215, v3, s[100:101]
	v_cmp_lt_i32_e64 s[0:1], 39, v38
	v_cmp_lt_i32_e64 s[100:101], 40, v38
	v_max3_f32 v39, v39, v2, v3
	v_cndmask_b32_e64 v4, v215, v4, s[0:1]
	v_cndmask_b32_e64 v5, v215, v5, s[100:101]
	v_cmp_lt_i32_e64 s[0:1], 41, v38
	v_cmp_lt_i32_e64 s[100:101], 42, v38
	v_max3_f32 v39, v39, v4, v5
	v_cndmask_b32_e64 v6, v215, v6, s[0:1]
	v_cndmask_b32_e64 v7, v215, v7, s[100:101]
	v_cmp_lt_i32_e64 s[0:1], 47, v38
	v_cmp_lt_i32_e64 s[100:101], 48, v38
	v_max3_f32 v39, v39, v6, v7
	v_cndmask_b32_e64 v8, v215, v8, s[0:1]
	v_cndmask_b32_e64 v9, v215, v9, s[100:101]
	v_cmp_lt_i32_e64 s[0:1], 49, v38
	v_cmp_lt_i32_e64 s[100:101], 50, v38
	v_max3_f32 v39, v39, v8, v9
	v_cndmask_b32_e64 v10, v215, v10, s[0:1]
	v_cndmask_b32_e64 v11, v215, v11, s[100:101]
	v_cmp_lt_i32_e64 s[0:1], 55, v38
	v_cmp_lt_i32_e64 s[100:101], 56, v38
	v_max3_f32 v39, v39, v10, v11
	v_cndmask_b32_e64 v12, v215, v12, s[0:1]
	v_cndmask_b32_e64 v13, v215, v13, s[100:101]
	v_cmp_lt_i32_e64 s[0:1], 57, v38
	v_cmp_lt_i32_e64 s[100:101], 58, v38
	v_max3_f32 v39, v39, v12, v13
	v_cndmask_b32_e64 v14, v215, v14, s[0:1]
	v_cndmask_b32_e64 v15, v215, v15, s[100:101]
	v_max3_f32 v38, v39, v14, v15
	ds_bpermute_b32 v39, v165, v38
	s_waitcnt lgkmcnt(0)
	v_max3_f32 v75, v42, v38, v39
	v_cmp_lt_f32_e64 s[0:1], s33, v75
	v_sub_f32_e32 v38, v42, v75
	v_exp_f32_e32 v38, v38
	v_cndmask_b32_e64 v40, 0, v75, s[0:1]
	v_sub_f32_e32 v16, v16, v40
	v_exp_f32_e32 v16, v16
	v_sub_f32_e32 v17, v17, v40
	v_exp_f32_e32 v17, v17
	v_sub_f32_e32 v18, v18, v40
	v_exp_f32_e32 v18, v18
	v_sub_f32_e32 v19, v19, v40
	v_exp_f32_e32 v19, v19
	v_sub_f32_e32 v20, v20, v40
	v_exp_f32_e32 v20, v20
	v_sub_f32_e32 v21, v21, v40
	v_exp_f32_e32 v21, v21
	v_sub_f32_e32 v22, v22, v40
	v_exp_f32_e32 v22, v22
	v_sub_f32_e32 v23, v23, v40
	v_exp_f32_e32 v23, v23
	v_sub_f32_e32 v24, v24, v40
	v_exp_f32_e32 v24, v24
	v_sub_f32_e32 v25, v25, v40
	v_exp_f32_e32 v25, v25
	v_sub_f32_e32 v26, v26, v40
	v_exp_f32_e32 v26, v26
	v_sub_f32_e32 v27, v27, v40
	v_exp_f32_e32 v27, v27
	v_sub_f32_e32 v28, v28, v40
	v_exp_f32_e32 v28, v28
	v_sub_f32_e32 v29, v29, v40
	v_exp_f32_e32 v29, v29
	v_sub_f32_e32 v30, v30, v40
	v_exp_f32_e32 v30, v30
	v_sub_f32_e32 v31, v31, v40
	v_exp_f32_e32 v31, v31
	v_sub_f32_e32 v0, v0, v40
	v_exp_f32_e32 v0, v0
	v_sub_f32_e32 v1, v1, v40
	v_exp_f32_e32 v1, v1
	v_sub_f32_e32 v2, v2, v40
	v_exp_f32_e32 v2, v2
	v_sub_f32_e32 v3, v3, v40
	v_exp_f32_e32 v3, v3
	v_sub_f32_e32 v4, v4, v40
	v_exp_f32_e32 v4, v4
	v_sub_f32_e32 v5, v5, v40
	v_exp_f32_e32 v5, v5
	v_sub_f32_e32 v6, v6, v40
	v_exp_f32_e32 v6, v6
	v_sub_f32_e32 v7, v7, v40
	v_exp_f32_e32 v7, v7
	v_sub_f32_e32 v8, v8, v40
	v_exp_f32_e32 v8, v8
	v_sub_f32_e32 v9, v9, v40
	v_exp_f32_e32 v9, v9
	v_sub_f32_e32 v10, v10, v40
	v_exp_f32_e32 v10, v10
	v_sub_f32_e32 v11, v11, v40
	v_exp_f32_e32 v11, v11
	v_sub_f32_e32 v12, v12, v40
	v_exp_f32_e32 v12, v12
	v_sub_f32_e32 v13, v13, v40
	v_exp_f32_e32 v13, v13
	v_sub_f32_e32 v14, v14, v40
	v_exp_f32_e32 v14, v14
	v_sub_f32_e32 v15, v15, v40
	v_exp_f32_e32 v15, v15
	v_add_f32_e32 v39, 0, v16
	v_add_f32_e32 v39, v17, v39
	v_add_f32_e32 v39, v18, v39
	v_add_f32_e32 v39, v19, v39
	v_add_f32_e32 v39, v20, v39
	v_add_f32_e32 v39, v21, v39
	v_add_f32_e32 v39, v22, v39
	v_add_f32_e32 v39, v23, v39
	v_add_f32_e32 v39, v24, v39
	v_add_f32_e32 v39, v25, v39
	v_add_f32_e32 v39, v26, v39
	v_add_f32_e32 v39, v27, v39
	v_add_f32_e32 v39, v28, v39
	v_add_f32_e32 v39, v29, v39
	v_add_f32_e32 v39, v30, v39
	v_add_f32_e32 v39, v31, v39
	v_add_f32_e32 v39, v0, v39
	v_add_f32_e32 v39, v1, v39
	v_add_f32_e32 v39, v2, v39
	v_add_f32_e32 v39, v3, v39
	v_add_f32_e32 v39, v4, v39
	v_add_f32_e32 v39, v5, v39
	v_add_f32_e32 v39, v6, v39
	v_add_f32_e32 v39, v7, v39
	v_add_f32_e32 v39, v8, v39
	v_add_f32_e32 v39, v9, v39
	v_add_f32_e32 v39, v10, v39
	v_add_f32_e32 v39, v11, v39
	v_add_f32_e32 v39, v12, v39
	v_add_f32_e32 v39, v13, v39
	v_add_f32_e32 v39, v14, v39
	v_add_f32_e32 v0, v15, v39
	s_mov_b64 s[0:1], 0
	v_fmac_f32_e32 v0, v32, v38
	s_cbranch_vccz .LBB0_794
	s_mov_b64 s[16:17], s[14:15]
	s_add_i32 s0, s16, 1
	s_mov_b32 s31, 0xf149f2ca
	s_cmp_eq_u32 s16, s10
	s_cbranch_scc1 .LBB0_797
	s_mov_b32 s16, s0
	s_branch .LBB0_793
